# leader's L1 invalidate moved off the release path: issued after the top-level arrival returns, release no longer waits for it
# speedup vs baseline: 1.0053x; 1.0053x over previous
.LBB0_184:
	s_andn2_saveexec_b64 s[8:9], s[8:9]
	s_cbranch_execz .LBB0_204
	s_mov_b64 s[8:9], exec
	s_nop 0
	s_nop 0
	s_waitcnt lgkmcnt(0)
	s_waitcnt vmcnt(0)
	v_mbcnt_lo_u32_b32 v2, s8, 0
	v_mbcnt_hi_u32_b32 v2, s9, v2
	v_cmp_eq_u32_e32 vcc, 0, v2
	s_and_saveexec_b64 s[10:11], vcc
	s_cbranch_execz .LBB0_187
	s_bcnt1_i32_b64 s8, s[8:9]
	v_mov_b32_e32 v3, 0x7000
	v_mov_b32_e32 v4, s8
	global_atomic_add v3, v3, v4, s[46:47] offset:1024 sc0
.LBB0_187:
	s_or_b64 exec, exec, s[10:11]
	v_cvt_f32_u32_e32 v4, v1
	s_waitcnt vmcnt(0)
	buffer_inv sc1
	v_readfirstlane_b32 s8, v3
	s_add_u32 s10, s46, 0x7500
	s_addc_u32 s11, s47, 0
	v_rcp_iflag_f32_e32 v4, v4
	v_add_u32_e32 v2, s8, v2
	v_add_u32_e32 v5, 1, v2
	s_mov_b64 s[12:13], -1
	v_mul_f32_e32 v3, 0x4f7ffffe, v4
	v_cvt_u32_f32_e32 v3, v3
	v_sub_u32_e32 v4, 0, v1
	v_mul_lo_u32 v4, v4, v3
	v_mul_hi_u32 v4, v3, v4
	v_add_u32_e32 v3, v3, v4
	v_mul_hi_u32 v3, v2, v3
	v_mul_lo_u32 v4, v3, v1
	v_sub_u32_e32 v2, v2, v4
	v_add_u32_e32 v6, 1, v3
	v_cmp_ge_u32_e32 vcc, v2, v1
	v_sub_u32_e32 v4, v2, v1
	s_nop 0
	v_cndmask_b32_e32 v3, v3, v6, vcc
	v_cndmask_b32_e32 v2, v2, v4, vcc
	v_add_u32_e32 v4, 1, v3
	v_cmp_ge_u32_e32 vcc, v2, v1
	s_nop 1
	v_cndmask_b32_e32 v4, v3, v4, vcc
	v_mul_lo_u32 v2, v1, v4
	v_add_u32_e32 v1, v2, v1
	v_cmp_ne_u32_e32 vcc, v5, v1
	v_mov_b64_e32 v[2:3], s[10:11]
	s_and_saveexec_b64 s[8:9], vcc
	s_cbranch_execz .LBB0_199
	v_mov_b32_e32 v1, 0
	global_load_dword v2, v1, s[10:11] sc1
	s_mov_b64 s[16:17], 0
	s_waitcnt vmcnt(0)
	v_cmp_eq_u32_e32 vcc, v2, v4
	s_and_saveexec_b64 s[14:15], vcc
	s_cbranch_execz .LBB0_198
	s_add_u32 s12, s46, 0x4200
	s_addc_u32 s13, s47, 0
	s_mov_b32 s30, 1
	s_branch .LBB0_191

.LBB0_201:
	s_or_b64 exec, exec, s[8:9]
	s_mov_b64 s[8:9], exec
	v_mbcnt_lo_u32_b32 v1, s8, 0
	v_mbcnt_hi_u32_b32 v1, s9, v1
	v_cmp_eq_u32_e32 vcc, 0, v1
	s_nop 0
	s_nop 0
	s_and_saveexec_b64 s[10:11], vcc
	s_cbranch_execz .LBB0_203
	s_bcnt1_i32_b64 s8, s[8:9]
	v_mov_b32_e32 v1, 0x2000
	v_mov_b32_e32 v2, s8
	global_atomic_add v1, v2, s[6:7] offset:1024

.LBB0_279:
	s_andn2_saveexec_b64 s[6:7], s[6:7]
	s_cbranch_execz .LBB0_299
	s_mov_b64 s[6:7], exec
	s_nop 0
	s_nop 0
	s_waitcnt lgkmcnt(0)
	s_waitcnt vmcnt(0)
	v_mbcnt_lo_u32_b32 v2, s6, 0
	v_mbcnt_hi_u32_b32 v2, s7, v2
	v_cmp_eq_u32_e32 vcc, 0, v2
	s_and_saveexec_b64 s[8:9], vcc
	s_cbranch_execz .LBB0_282
	s_bcnt1_i32_b64 s6, s[6:7]
	v_mov_b32_e32 v3, 0x7000
	v_mov_b32_e32 v4, s6
	global_atomic_add v3, v3, v4, s[46:47] offset:1024 sc0
.LBB0_282:
	s_or_b64 exec, exec, s[8:9]
	v_cvt_f32_u32_e32 v4, v1
	s_waitcnt vmcnt(0)
	buffer_inv sc1
	v_readfirstlane_b32 s6, v3
	s_add_u32 s8, s46, 0x7500
	s_addc_u32 s9, s47, 0
	v_rcp_iflag_f32_e32 v4, v4
	v_add_u32_e32 v2, s6, v2
	v_add_u32_e32 v5, 1, v2
	s_mov_b64 s[10:11], -1
	v_mul_f32_e32 v3, 0x4f7ffffe, v4
	v_cvt_u32_f32_e32 v3, v3
	v_sub_u32_e32 v4, 0, v1
	v_mul_lo_u32 v4, v4, v3
	v_mul_hi_u32 v4, v3, v4
	v_add_u32_e32 v3, v3, v4
	v_mul_hi_u32 v3, v2, v3
	v_mul_lo_u32 v4, v3, v1
	v_sub_u32_e32 v2, v2, v4
	v_add_u32_e32 v6, 1, v3
	v_cmp_ge_u32_e32 vcc, v2, v1
	v_sub_u32_e32 v4, v2, v1
	s_nop 0
	v_cndmask_b32_e32 v3, v3, v6, vcc
	v_cndmask_b32_e32 v2, v2, v4, vcc
	v_add_u32_e32 v4, 1, v3
	v_cmp_ge_u32_e32 vcc, v2, v1
	s_nop 1
	v_cndmask_b32_e32 v4, v3, v4, vcc
	v_mul_lo_u32 v2, v1, v4
	v_add_u32_e32 v1, v2, v1
	v_cmp_ne_u32_e32 vcc, v5, v1
	v_mov_b64_e32 v[2:3], s[8:9]
	s_and_saveexec_b64 s[6:7], vcc
	s_cbranch_execz .LBB0_294
	v_mov_b32_e32 v1, 0
	global_load_dword v2, v1, s[8:9] sc1
	s_mov_b64 s[14:15], 0
	s_waitcnt vmcnt(0)
	v_cmp_eq_u32_e32 vcc, v2, v4
	s_and_saveexec_b64 s[12:13], vcc
	s_cbranch_execz .LBB0_293
	s_add_u32 s10, s46, 0x4200
	s_addc_u32 s11, s47, 0
	s_mov_b32 s26, 1
	s_branch .LBB0_286

.LBB0_296:
	s_or_b64 exec, exec, s[6:7]
	s_mov_b64 s[6:7], exec
	v_mbcnt_lo_u32_b32 v1, s6, 0
	v_mbcnt_hi_u32_b32 v1, s7, v1
	v_cmp_eq_u32_e32 vcc, 0, v1
	s_nop 0
	s_nop 0
	s_and_saveexec_b64 s[8:9], vcc
	s_cbranch_execz .LBB0_298
	s_bcnt1_i32_b64 s6, s[6:7]
	v_mov_b32_e32 v1, 0x2000
	v_mov_b32_e32 v2, s6
	global_atomic_add v1, v2, s[4:5] offset:1024

.LBB0_398:
	s_andn2_saveexec_b64 s[14:15], s[14:15]
	s_cbranch_execz .LBB0_418
	s_mov_b64 s[14:15], exec
	buffer_wbl2 sc1
	s_nop 0
	s_waitcnt lgkmcnt(0)
	s_waitcnt vmcnt(0)
	v_mbcnt_lo_u32_b32 v3, s14, 0
	v_mbcnt_hi_u32_b32 v3, s15, v3
	v_cmp_eq_u32_e32 vcc, 0, v3
	s_and_saveexec_b64 s[20:21], vcc
	s_cbranch_execz .LBB0_401
	s_bcnt1_i32_b64 s4, s[14:15]
	v_mov_b32_e32 v4, s4
	v_readlane_b32 s4, v253, 42
	v_readlane_b32 s5, v253, 43
	s_nop 4
	global_atomic_add v4, v99, v4, s[4:5] sc0
.LBB0_401:
	s_or_b64 exec, exec, s[20:21]
	s_waitcnt vmcnt(0)
	buffer_inv sc1
	v_readfirstlane_b32 s4, v4
	v_cvt_f32_u32_e32 v4, v2
	v_sub_u32_e32 v5, 0, v2
	v_add_u32_e32 v3, s4, v3
	v_readlane_b32 s4, v253, 44
	v_rcp_iflag_f32_e32 v4, v4
	v_readlane_b32 s5, v253, 45
	s_mov_b64 s[20:21], -1
	v_mul_f32_e32 v4, 0x4f7ffffe, v4
	v_cvt_u32_f32_e32 v4, v4
	v_mul_lo_u32 v5, v5, v4
	v_mul_hi_u32 v5, v4, v5
	v_add_u32_e32 v4, v4, v5
	v_mul_hi_u32 v4, v3, v4
	v_mul_lo_u32 v5, v4, v2
	v_sub_u32_e32 v5, v3, v5
	v_cmp_ge_u32_e32 vcc, v5, v2
	v_add_u32_e32 v6, 1, v4
	v_add_u32_e32 v3, 1, v3
	v_cndmask_b32_e32 v4, v4, v6, vcc
	v_sub_u32_e32 v6, v5, v2
	v_cndmask_b32_e32 v5, v5, v6, vcc
	v_cmp_ge_u32_e32 vcc, v5, v2
	v_add_u32_e32 v5, 1, v4
	s_nop 0
	v_cndmask_b32_e32 v4, v4, v5, vcc
	v_mul_lo_u32 v5, v2, v4
	v_add_u32_e32 v2, v5, v2
	v_cmp_ne_u32_e32 vcc, v3, v2
	v_mov_b64_e32 v[2:3], s[4:5]
	s_and_saveexec_b64 s[14:15], vcc
	s_cbranch_execz .LBB0_413
	v_readlane_b32 s4, v253, 44
	v_readlane_b32 s5, v253, 45
	s_mov_b64 s[30:31], 0
	s_nop 3
	global_load_dword v2, v99, s[4:5] sc1
	s_waitcnt vmcnt(0)
	v_cmp_eq_u32_e32 vcc, v2, v4
	s_and_saveexec_b64 s[20:21], vcc
	s_cbranch_execz .LBB0_412
	s_mov_b32 s18, 1
	s_branch .LBB0_405

.LBB0_415:
	s_or_b64 exec, exec, s[14:15]
	s_mov_b64 s[14:15], exec
	v_mbcnt_lo_u32_b32 v2, s14, 0
	v_mbcnt_hi_u32_b32 v2, s15, v2
	v_cmp_eq_u32_e32 vcc, 0, v2
	s_nop 0
	s_nop 0
	s_and_saveexec_b64 s[20:21], vcc
	s_cbranch_execz .LBB0_417
	s_bcnt1_i32_b64 s4, s[14:15]
	v_mov_b32_e32 v2, s4
	v_readlane_b32 s4, v253, 40
	v_readlane_b32 s5, v253, 41
	s_nop 4
	global_atomic_add v99, v2, s[4:5]

.LBB0_537:
	s_andn2_saveexec_b64 s[10:11], s[10:11]
	s_cbranch_execz .LBB0_557
	s_mov_b64 s[10:11], exec
	buffer_wbl2 sc1
	s_nop 0
	s_waitcnt lgkmcnt(0)
	s_waitcnt vmcnt(0)
	v_mbcnt_lo_u32_b32 v3, s10, 0
	v_mbcnt_hi_u32_b32 v3, s11, v3
	v_cmp_eq_u32_e32 vcc, 0, v3
	s_and_saveexec_b64 s[12:13], vcc
	s_cbranch_execz .LBB0_540
	s_bcnt1_i32_b64 s4, s[10:11]
	v_mov_b32_e32 v4, s4
	v_readlane_b32 s4, v253, 42
	v_readlane_b32 s5, v253, 43
	s_nop 4
	global_atomic_add v4, v99, v4, s[4:5] sc0
.LBB0_540:
	s_or_b64 exec, exec, s[12:13]
	s_waitcnt vmcnt(0)
	buffer_inv sc1
	v_readfirstlane_b32 s4, v4
	v_cvt_f32_u32_e32 v4, v2
	v_sub_u32_e32 v5, 0, v2
	v_add_u32_e32 v3, s4, v3
	v_readlane_b32 s4, v253, 44
	v_rcp_iflag_f32_e32 v4, v4
	v_readlane_b32 s5, v253, 45
	s_mov_b64 s[12:13], -1
	v_mul_f32_e32 v4, 0x4f7ffffe, v4
	v_cvt_u32_f32_e32 v4, v4
	v_mul_lo_u32 v5, v5, v4
	v_mul_hi_u32 v5, v4, v5
	v_add_u32_e32 v4, v4, v5
	v_mul_hi_u32 v4, v3, v4
	v_mul_lo_u32 v5, v4, v2
	v_sub_u32_e32 v5, v3, v5
	v_cmp_ge_u32_e32 vcc, v5, v2
	v_add_u32_e32 v6, 1, v4
	v_add_u32_e32 v3, 1, v3
	v_cndmask_b32_e32 v4, v4, v6, vcc
	v_sub_u32_e32 v6, v5, v2
	v_cndmask_b32_e32 v5, v5, v6, vcc
	v_cmp_ge_u32_e32 vcc, v5, v2
	v_add_u32_e32 v5, 1, v4
	s_nop 0
	v_cndmask_b32_e32 v4, v4, v5, vcc
	v_mul_lo_u32 v5, v2, v4
	v_add_u32_e32 v2, v5, v2
	v_cmp_ne_u32_e32 vcc, v3, v2
	v_mov_b64_e32 v[2:3], s[4:5]
	s_and_saveexec_b64 s[10:11], vcc
	s_cbranch_execz .LBB0_552
	v_readlane_b32 s4, v253, 44
	v_readlane_b32 s5, v253, 45
	s_mov_b64 s[14:15], 0
	s_nop 3
	global_load_dword v2, v99, s[4:5] sc1
	s_waitcnt vmcnt(0)
	v_cmp_eq_u32_e32 vcc, v2, v4
	s_and_saveexec_b64 s[12:13], vcc
	s_cbranch_execz .LBB0_551
	s_mov_b32 s27, 1
	s_branch .LBB0_544

.LBB0_554:
	s_or_b64 exec, exec, s[10:11]
	s_mov_b64 s[10:11], exec
	v_mbcnt_lo_u32_b32 v2, s10, 0
	v_mbcnt_hi_u32_b32 v2, s11, v2
	v_cmp_eq_u32_e32 vcc, 0, v2
	s_nop 0
	s_nop 0
	s_and_saveexec_b64 s[12:13], vcc
	s_cbranch_execz .LBB0_556
	s_bcnt1_i32_b64 s4, s[10:11]
	v_mov_b32_e32 v2, s4
	v_readlane_b32 s4, v253, 40
	v_readlane_b32 s5, v253, 41
	s_nop 4
	global_atomic_add v99, v2, s[4:5]

.LBB0_968:
	s_andn2_saveexec_b64 s[4:5], s[12:13]
	s_cbranch_execz .LBB0_988
	s_mov_b64 s[12:13], exec
	buffer_wbl2 sc1
	s_nop 0
	s_waitcnt lgkmcnt(0)
	s_waitcnt vmcnt(0)
	v_mbcnt_lo_u32_b32 v3, s12, 0
	v_mbcnt_hi_u32_b32 v3, s13, v3
	v_cmp_eq_u32_e32 vcc, 0, v3
	s_and_saveexec_b64 s[14:15], vcc
	s_cbranch_execz .LBB0_971
	s_bcnt1_i32_b64 s4, s[12:13]
	v_mov_b32_e32 v4, s4
	v_readlane_b32 s4, v253, 42
	v_readlane_b32 s5, v253, 43
	s_nop 4
	global_atomic_add v4, v99, v4, s[4:5] sc0
.LBB0_971:
	s_or_b64 exec, exec, s[14:15]
	s_waitcnt vmcnt(0)
	buffer_inv sc1
	v_readfirstlane_b32 s4, v4
	v_cvt_f32_u32_e32 v4, v2
	v_sub_u32_e32 v5, 0, v2
	v_add_u32_e32 v3, s4, v3
	v_readlane_b32 s4, v253, 44
	v_rcp_iflag_f32_e32 v4, v4
	v_readlane_b32 s5, v253, 45
	s_mov_b64 s[14:15], -1
	v_mul_f32_e32 v4, 0x4f7ffffe, v4
	v_cvt_u32_f32_e32 v4, v4
	v_mul_lo_u32 v5, v5, v4
	v_mul_hi_u32 v5, v4, v5
	v_add_u32_e32 v4, v4, v5
	v_mul_hi_u32 v4, v3, v4
	v_mul_lo_u32 v5, v4, v2
	v_sub_u32_e32 v5, v3, v5
	v_cmp_ge_u32_e32 vcc, v5, v2
	v_add_u32_e32 v6, 1, v4
	v_add_u32_e32 v3, 1, v3
	v_cndmask_b32_e32 v4, v4, v6, vcc
	v_sub_u32_e32 v6, v5, v2
	v_cndmask_b32_e32 v5, v5, v6, vcc
	v_cmp_ge_u32_e32 vcc, v5, v2
	v_add_u32_e32 v5, 1, v4
	s_nop 0
	v_cndmask_b32_e32 v4, v4, v5, vcc
	v_mul_lo_u32 v5, v2, v4
	v_add_u32_e32 v2, v5, v2
	v_cmp_ne_u32_e32 vcc, v3, v2
	v_mov_b64_e32 v[2:3], s[4:5]
	s_and_saveexec_b64 s[12:13], vcc
	s_cbranch_execz .LBB0_983
	v_readlane_b32 s4, v253, 44
	v_readlane_b32 s5, v253, 45
	s_mov_b64 s[20:21], 0
	s_nop 3
	global_load_dword v2, v99, s[4:5] sc1
	s_waitcnt vmcnt(0)
	v_cmp_eq_u32_e32 vcc, v2, v4
	s_and_saveexec_b64 s[14:15], vcc
	s_cbranch_execz .LBB0_982
	s_mov_b32 s27, 1
	s_branch .LBB0_975

.LBB0_985:
	s_or_b64 exec, exec, s[12:13]
	s_mov_b64 s[12:13], exec
	v_mbcnt_lo_u32_b32 v2, s12, 0
	v_mbcnt_hi_u32_b32 v2, s13, v2
	v_cmp_eq_u32_e32 vcc, 0, v2
	s_nop 0
	s_nop 0
	s_and_saveexec_b64 s[14:15], vcc
	s_cbranch_execz .LBB0_987
	s_bcnt1_i32_b64 s4, s[12:13]
	v_mov_b32_e32 v2, s4
	v_readlane_b32 s4, v253, 40
	v_readlane_b32 s5, v253, 41
	s_nop 4
	global_atomic_add v99, v2, s[4:5]

.Lmy_xl_rel:
	s_mov_b64 s[10:11], exec
	v_mbcnt_lo_u32_b32 v2, s10, 0
	v_mbcnt_hi_u32_b32 v2, s11, v2
	v_cmp_eq_u32_e32 vcc, 0, v2
	s_nop 0
	s_nop 0
	s_and_saveexec_b64 s[14:15], vcc
	s_cbranch_execz .LBB0_1080
	s_bcnt1_i32_b64 s4, s[10:11]
	v_mov_b32_e32 v2, s4
	v_readlane_b32 s4, v253, 40
	v_readlane_b32 s5, v253, 41
	s_nop 4
	global_atomic_add v99, v2, s[4:5]

.LBB0_1264:
	s_andn2_saveexec_b64 s[4:5], s[14:15]
	s_cbranch_execz .LBB0_1301
	s_mov_b64 s[14:15], exec
	buffer_wbl2 sc1
	s_nop 0
	s_waitcnt lgkmcnt(0)
	s_waitcnt vmcnt(0)
	v_mbcnt_lo_u32_b32 v3, s14, 0
	v_mbcnt_hi_u32_b32 v3, s15, v3
	v_cmp_eq_u32_e32 vcc, 0, v3
	s_and_saveexec_b64 s[20:21], vcc
	s_cbranch_execz .LBB0_1267
	s_bcnt1_i32_b64 s4, s[14:15]
	v_mov_b32_e32 v4, s4
	v_readlane_b32 s4, v253, 42
	v_readlane_b32 s5, v253, 43
	s_nop 4
	global_atomic_add v4, v99, v4, s[4:5] sc0
.LBB0_1267:
	s_or_b64 exec, exec, s[20:21]
	s_waitcnt vmcnt(0)
	buffer_inv sc1
	v_readfirstlane_b32 s4, v4
	v_cvt_f32_u32_e32 v4, v2
	v_sub_u32_e32 v5, 0, v2
	v_add_u32_e32 v3, s4, v3
	v_readlane_b32 s4, v253, 44
	v_rcp_iflag_f32_e32 v4, v4
	v_readlane_b32 s5, v253, 45
	s_mov_b64 s[20:21], -1
	v_mul_f32_e32 v4, 0x4f7ffffe, v4
	v_cvt_u32_f32_e32 v4, v4
	v_mul_lo_u32 v5, v5, v4
	v_mul_hi_u32 v5, v4, v5
	v_add_u32_e32 v4, v4, v5
	v_mul_hi_u32 v4, v3, v4
	v_mul_lo_u32 v5, v4, v2
	v_sub_u32_e32 v5, v3, v5
	v_cmp_ge_u32_e32 vcc, v5, v2
	v_add_u32_e32 v6, 1, v4
	v_add_u32_e32 v3, 1, v3
	v_cndmask_b32_e32 v4, v4, v6, vcc
	v_sub_u32_e32 v6, v5, v2
	v_cndmask_b32_e32 v5, v5, v6, vcc
	v_cmp_ge_u32_e32 vcc, v5, v2
	v_add_u32_e32 v5, 1, v4
	s_nop 0
	v_cndmask_b32_e32 v4, v4, v5, vcc
	v_mul_lo_u32 v5, v2, v4
	v_add_u32_e32 v2, v5, v2
	v_cmp_ne_u32_e32 vcc, v3, v2
	v_mov_b64_e32 v[2:3], s[4:5]
	s_and_saveexec_b64 s[14:15], vcc
	s_cbranch_execz .LBB0_1296
	v_readlane_b32 s4, v253, 44
	v_readlane_b32 s5, v253, 45
	s_mov_b64 s[26:27], 0
	s_nop 3
	global_load_dword v2, v99, s[4:5] sc1
	s_waitcnt vmcnt(0)
	v_cmp_eq_u32_e32 vcc, v2, v4
	s_and_saveexec_b64 s[20:21], vcc
	s_cbranch_execz .LBB0_1295
	s_mov_b32 s18, 1
	s_branch .LBB0_1271

.LBB0_1281:
	s_andn2_saveexec_b64 s[4:5], s[10:11]
	s_cbranch_execz .LBB0_1309
	s_mov_b64 s[10:11], exec
	buffer_wbl2 sc1
	s_nop 0
	s_waitcnt lgkmcnt(0)
	s_waitcnt vmcnt(0)
	v_mbcnt_lo_u32_b32 v3, s10, 0
	v_mbcnt_hi_u32_b32 v3, s11, v3
	v_cmp_eq_u32_e32 vcc, 0, v3
	s_and_saveexec_b64 s[12:13], vcc
	s_cbranch_execz .LBB0_1284
	s_bcnt1_i32_b64 s4, s[10:11]
	v_mov_b32_e32 v4, s4
	v_readlane_b32 s4, v253, 42
	v_readlane_b32 s5, v253, 43
	s_nop 4
	global_atomic_add v4, v99, v4, s[4:5] sc0
.LBB0_1284:
	s_or_b64 exec, exec, s[12:13]
	s_waitcnt vmcnt(0)
	buffer_inv sc1
	v_readfirstlane_b32 s4, v4
	v_cvt_f32_u32_e32 v4, v2
	v_sub_u32_e32 v5, 0, v2
	v_add_u32_e32 v3, s4, v3
	v_readlane_b32 s4, v253, 44
	v_rcp_iflag_f32_e32 v4, v4
	v_readlane_b32 s5, v253, 45
	s_mov_b64 s[12:13], -1
	v_mul_f32_e32 v4, 0x4f7ffffe, v4
	v_cvt_u32_f32_e32 v4, v4
	v_mul_lo_u32 v5, v5, v4
	v_mul_hi_u32 v5, v4, v5
	v_add_u32_e32 v4, v4, v5
	v_mul_hi_u32 v4, v3, v4
	v_mul_lo_u32 v5, v4, v2
	v_sub_u32_e32 v5, v3, v5
	v_cmp_ge_u32_e32 vcc, v5, v2
	v_add_u32_e32 v6, 1, v4
	v_add_u32_e32 v3, 1, v3
	v_cndmask_b32_e32 v4, v4, v6, vcc
	v_sub_u32_e32 v6, v5, v2
	v_cndmask_b32_e32 v5, v5, v6, vcc
	v_cmp_ge_u32_e32 vcc, v5, v2
	v_add_u32_e32 v5, 1, v4
	s_nop 0
	v_cndmask_b32_e32 v4, v4, v5, vcc
	v_mul_lo_u32 v5, v2, v4
	v_add_u32_e32 v2, v5, v2
	v_cmp_ne_u32_e32 vcc, v3, v2
	v_mov_b64_e32 v[2:3], s[4:5]
	s_and_saveexec_b64 s[10:11], vcc
	s_cbranch_execz .LBB0_1304
	v_readlane_b32 s4, v253, 44
	v_readlane_b32 s5, v253, 45
	s_mov_b64 s[14:15], 0
	s_nop 3
	global_load_dword v2, v99, s[4:5] sc1
	s_waitcnt vmcnt(0)
	v_cmp_eq_u32_e32 vcc, v2, v4
	s_and_saveexec_b64 s[12:13], vcc
	s_cbranch_execz .LBB0_1303
	s_mov_b32 s18, 1
	s_branch .LBB0_1288
